# dilated attention fast path: PV accumulates in place (32 register copies per 64-key step removed), on top of dilated PV prefetch and FFN-up epilogue rewrite
# speedup vs baseline: 1.0138x; 1.0138x over previous
; #define LAS __attribute__((address_space(3)))
; #define MFMA32(a, b, c) __builtin_amdgcn_mfma_f32_32x32x16_bf16((a), (b), (c), 0, 0, 0)
;     ...
;     for (int r = 0; r < 16; ++r) {
;         float e0 = __builtin_amdgcn_exp2f(p0[r]), e1 = __builtin_amdgcn_exp2f(p1[r]);
;         if (WMODE == 1) { e0 *= wa[r]; e1 *= wa[r]; }
;         if (WMODE == 4) { const int d0 = dlt0 - ((r & 3) + 8 * (r >> 2)), d1 = d0 - 32;
;             const float w0 = (((unsigned)d0 <= 128u) ? 1.f : 0.f) + ((((unsigned)d0 <= 512u) && ((d0 & 3) == 0)) ? 1.f : 0.f) + ((((unsigned)d0 <= 2048u) && ((d0 & 15) == 0)) ? 1.f : 0.f);
;             const float w1 = (((unsigned)d1 <= 128u) ? 1.f : 0.f) + ((((unsigned)d1 <= 512u) && ((d1 & 3) == 0)) ? 1.f : 0.f) + ((((unsigned)d1 <= 2048u) && ((d1 & 15) == 0)) ? 1.f : 0.f);
;             e0 *= w0; e1 *= w1; }
;         p0[r] = e0; p1[r] = e1; s0 += e0; s1 += e1; }
;     l += s0 + s1;
; template <int MODE> __device__ __forceinline__ void attn_unit(LAS unsigned char* lds, const AttnP& P, int b, int h, int qb) {
;     ...
;     auto pv = [&](const int voff) __attribute__((always_inline)) {
;         const LAS unsigned char* vb_ = lds + L_V + voff + r32 * VROWB + hi * 16;
; #pragma unroll
;         for (int j = 0; j < 4; ++j) { const bf16x8 v0 = *(const LAS bf16x8*)(vb_ + j * 32), v1 = *(const LAS bf16x8*)(vb_ + 32 * VROWB + j * 32);
;             oa0 = MFMA32(v0, pa[j], oa0); oa1 = MFMA32(v1, pa[j], oa1);
;             if (MODE == 1) { ob0 = MFMA32(v0, pb[j], ob0); ob1 = MFMA32(v1, pb[j], ob1); } }
;     };
.LBB0_767:
	v_exp_f32_e32 v99, v66
	v_exp_f32_e32 v98, v82
	v_exp_f32_e32 v67, v67
	v_exp_f32_e32 v66, v83
	v_exp_f32_e32 v83, v68
	v_exp_f32_e32 v82, v84
	v_exp_f32_e32 v69, v69
	v_exp_f32_e32 v68, v85
	s_waitcnt lgkmcnt(3)
	v_pk_fma_f32 v[84:85], v[62:63], v[98:99], 0 op_sel_hi:[0,1,0]
	v_pk_mul_f32 v[172:173], v[62:63], v[98:99] op_sel_hi:[0,1]
	v_pk_mul_f32 v[176:177], v[62:63], v[66:67] op_sel:[1,0]
	v_pk_fma_f32 v[62:63], v[62:63], v[66:67], v[84:85] op_sel:[1,0,0]
	v_pk_mul_f32 v[180:181], v[64:65], v[82:83] op_sel_hi:[0,1]
	v_pk_fma_f32 v[62:63], v[64:65], v[82:83], v[62:63] op_sel_hi:[0,1,1]
	v_exp_f32_e32 v67, v70
	v_exp_f32_e32 v66, v86
	v_mov_b32_e32 v64, v65
	v_pk_mul_f32 v[184:185], v[64:65], v[68:69] op_sel_hi:[0,1]
	v_pk_fma_f32 v[62:63], v[64:65], v[68:69], v[62:63] op_sel_hi:[0,1,1]
	v_exp_f32_e32 v65, v71
	v_exp_f32_e32 v64, v87
	v_exp_f32_e32 v69, v72
	v_exp_f32_e32 v68, v88
	v_exp_f32_e32 v71, v73
	v_exp_f32_e32 v70, v89
	v_exp_f32_e32 v73, v74
	v_exp_f32_e32 v72, v90
	s_waitcnt lgkmcnt(2)
	v_pk_fma_f32 v[62:63], v[58:59], v[66:67], v[62:63] op_sel_hi:[0,1,1]
	v_pk_mul_f32 v[188:189], v[58:59], v[66:67] op_sel_hi:[0,1]
	v_exp_f32_e32 v75, v75
	v_exp_f32_e32 v74, v91
	v_pk_mul_f32 v[204:205], v[58:59], v[64:65] op_sel:[1,0]
	v_pk_fma_f32 v[58:59], v[58:59], v[64:65], v[62:63] op_sel:[1,0,0]
	v_exp_f32_e32 v83, v76
	v_exp_f32_e32 v82, v92
	v_pk_mul_f32 v[208:209], v[60:61], v[68:69] op_sel_hi:[0,1]
	v_pk_fma_f32 v[58:59], v[60:61], v[68:69], v[58:59] op_sel_hi:[0,1,1]
	v_mov_b32_e32 v60, v61
	v_exp_f32_e32 v77, v77
	v_exp_f32_e32 v76, v93
	v_pk_fma_f32 v[58:59], v[60:61], v[70:71], v[58:59] op_sel_hi:[0,1,1]
	v_exp_f32_e32 v85, v78
	v_exp_f32_e32 v84, v94
	s_waitcnt lgkmcnt(1)
	v_pk_fma_f32 v[58:59], v[54:55], v[72:73], v[58:59] op_sel_hi:[0,1,1]
	v_exp_f32_e32 v79, v79
	v_exp_f32_e32 v78, v95
	v_pk_mul_f32 v[210:211], v[54:55], v[72:73] op_sel_hi:[0,1]
	v_pk_mul_f32 v[190:191], v[54:55], v[74:75] op_sel:[1,0]
	v_pk_fma_f32 v[54:55], v[54:55], v[74:75], v[58:59] op_sel:[1,0,0]
	v_exp_f32_e32 v87, v80
	v_exp_f32_e32 v86, v96
	v_pk_mul_f32 v[192:193], v[56:57], v[82:83] op_sel_hi:[0,1]
	v_pk_fma_f32 v[54:55], v[56:57], v[82:83], v[54:55] op_sel_hi:[0,1,1]
	v_mov_b32_e32 v56, v57
	v_exp_f32_e32 v81, v81
	v_exp_f32_e32 v80, v97
	v_pk_fma_f32 v[54:55], v[56:57], v[76:77], v[54:55] op_sel_hi:[0,1,1]
	s_waitcnt lgkmcnt(0)
	v_pk_fma_f32 v[54:55], v[50:51], v[84:85], v[54:55] op_sel_hi:[0,1,1]
	v_pk_mul_f32 v[186:187], v[50:51], v[84:85] op_sel_hi:[0,1]
	v_pk_mul_f32 v[174:175], v[50:51], v[78:79] op_sel:[1,0]
	v_pk_fma_f32 v[50:51], v[50:51], v[78:79], v[54:55] op_sel:[1,0,0]
	v_pk_mul_f32 v[178:179], v[52:53], v[86:87] op_sel_hi:[0,1]
	v_pk_fma_f32 v[50:51], v[52:53], v[86:87], v[50:51] op_sel_hi:[0,1,1]
	v_mov_b32_e32 v52, v53
	v_pk_fma_f32 v[50:51], v[52:53], v[80:81], v[50:51] op_sel_hi:[0,1,1]
	v_pk_mul_f32 v[206:207], v[60:61], v[70:71] op_sel_hi:[0,1]
	v_pk_mul_f32 v[182:183], v[56:57], v[76:77] op_sel_hi:[0,1]
	v_pk_mul_f32 v[168:169], v[52:53], v[80:81] op_sel_hi:[0,1]
	v_add_f32_e32 v170, v50, v51
	v_mov_b64_e32 v[64:65], v[48:49]
	v_mov_b64_e32 v[62:63], v[46:47]
	v_mov_b64_e32 v[60:61], v[44:45]
	v_mov_b64_e32 v[58:59], v[42:43]
	v_mov_b64_e32 v[56:57], v[40:41]
	v_mov_b64_e32 v[54:55], v[38:39]
	v_mov_b64_e32 v[52:53], v[36:37]
	v_mov_b64_e32 v[50:51], v[34:35]
	v_mov_b32_e32 v224, v223
	v_mov_b32_e32 v227, v222
	s_mul_i32 s0, s16, 0x4400
	v_add_u32_e32 v106, s0, v221
	ds_read_b128 v[98:101], v106 offset:36864
	ds_read_b128 v[232:235], v106 offset:45568
	ds_read_b128 v[236:239], v106 offset:36896
	v_cvt_pk_bf16_f32 v102, v173, v177
	v_cvt_pk_bf16_f32 v103, v181, v185
	v_cvt_pk_bf16_f32 v104, v189, v205
	v_cvt_pk_bf16_f32 v105, v209, v207
	v_add_f32_e32 v222, v227, v170
	s_mov_b64 s[0:1], 0
	s_waitcnt lgkmcnt(2)
	v_mfma_f32_32x32x16_bf16 v[18:33], v[98:101], v[102:105], v[18:33]
	ds_read_b128 v[98:101], v106 offset:45600
	s_waitcnt lgkmcnt(2)
	v_mfma_f32_32x32x16_bf16 v[2:17], v[232:235], v[102:105], v[2:17]
	ds_read_b128 v[232:235], v106 offset:36928
	v_cvt_pk_bf16_f32 v102, v211, v191
	v_cvt_pk_bf16_f32 v103, v193, v183
	v_cvt_pk_bf16_f32 v104, v187, v175
	v_cvt_pk_bf16_f32 v105, v179, v169
	s_nop 0
	s_waitcnt lgkmcnt(2)
	v_mfma_f32_32x32x16_bf16 v[18:33], v[236:239], v[102:105], v[18:33]
	ds_read_b128 v[236:239], v106 offset:45632
	s_waitcnt lgkmcnt(2)
	v_mfma_f32_32x32x16_bf16 v[2:17], v[98:101], v[102:105], v[2:17]
	ds_read_b128 v[98:101], v106 offset:36960
	v_cvt_pk_bf16_f32 v102, v172, v176
	v_cvt_pk_bf16_f32 v103, v180, v184
	v_cvt_pk_bf16_f32 v104, v188, v204
	v_cvt_pk_bf16_f32 v105, v208, v206
	s_nop 0
	s_waitcnt lgkmcnt(2)
	v_mfma_f32_32x32x16_bf16 v[18:33], v[232:235], v[102:105], v[18:33]
	ds_read_b128 v[232:235], v106 offset:45664
	s_waitcnt lgkmcnt(2)
	v_mfma_f32_32x32x16_bf16 v[2:17], v[236:239], v[102:105], v[2:17]
	v_cvt_pk_bf16_f32 v102, v210, v190
	v_cvt_pk_bf16_f32 v103, v192, v182
	v_cvt_pk_bf16_f32 v104, v186, v174
	v_cvt_pk_bf16_f32 v105, v178, v168
	s_nop 0
	s_waitcnt lgkmcnt(1)
	v_mfma_f32_32x32x16_bf16 v[18:33], v[98:101], v[102:105], v[18:33]
	s_waitcnt lgkmcnt(0)
	v_mfma_f32_32x32x16_bf16 v[2:17], v[232:235], v[102:105], v[2:17]
	s_nop 15
	s_nop 3
	s_branch .LBB0_769

; #define LAS __attribute__((address_space(3)))
; #define MFMA32(a, b, c) __builtin_amdgcn_mfma_f32_32x32x16_bf16((a), (b), (c), 0, 0, 0)
;     ...
;     for (int r = 0; r < 16; ++r) {
;         float e0 = __builtin_amdgcn_exp2f(p0[r]), e1 = __builtin_amdgcn_exp2f(p1[r]);
;         if (WMODE == 1) { e0 *= wa[r]; e1 *= wa[r]; }
;         if (WMODE == 4) { const int d0 = dlt0 - ((r & 3) + 8 * (r >> 2)), d1 = d0 - 32;
;             const float w0 = (((unsigned)d0 <= 128u) ? 1.f : 0.f) + ((((unsigned)d0 <= 512u) && ((d0 & 3) == 0)) ? 1.f : 0.f) + ((((unsigned)d0 <= 2048u) && ((d0 & 15) == 0)) ? 1.f : 0.f);
;             const float w1 = (((unsigned)d1 <= 128u) ? 1.f : 0.f) + ((((unsigned)d1 <= 512u) && ((d1 & 3) == 0)) ? 1.f : 0.f) + ((((unsigned)d1 <= 2048u) && ((d1 & 15) == 0)) ? 1.f : 0.f);
;             e0 *= w0; e1 *= w1; }
;         p0[r] = e0; p1[r] = e1; s0 += e0; s1 += e1; }
;     l += s0 + s1;
; template <int MODE> __device__ __forceinline__ void attn_unit(LAS unsigned char* lds, const AttnP& P, int b, int h, int qb) {
;     ...
;     auto pv = [&](const int voff) __attribute__((always_inline)) {
;         const LAS unsigned char* vb_ = lds + L_V + voff + r32 * VROWB + hi * 16;
; #pragma unroll
;         for (int j = 0; j < 4; ++j) { const bf16x8 v0 = *(const LAS bf16x8*)(vb_ + j * 32), v1 = *(const LAS bf16x8*)(vb_ + 32 * VROWB + j * 32);
;             oa0 = MFMA32(v0, pa[j], oa0); oa1 = MFMA32(v1, pa[j], oa1);
;             if (MODE == 1) { ob0 = MFMA32(v0, pb[j], ob0); ob1 = MFMA32(v1, pb[j], ob1); } }
;     };
.LBB0_790:
	v_exp_f32_e32 v99, v66
	v_exp_f32_e32 v98, v82
	v_exp_f32_e32 v67, v67
	v_exp_f32_e32 v66, v83
	v_exp_f32_e32 v83, v68
	v_exp_f32_e32 v82, v84
	v_exp_f32_e32 v69, v69
	v_exp_f32_e32 v68, v85
	s_waitcnt lgkmcnt(3)
	v_pk_fma_f32 v[84:85], v[46:47], v[98:99], 0 op_sel_hi:[0,1,0]
	v_pk_mul_f32 v[172:173], v[46:47], v[98:99] op_sel_hi:[0,1]
	v_pk_mul_f32 v[176:177], v[46:47], v[66:67] op_sel:[1,0]
	v_pk_fma_f32 v[46:47], v[46:47], v[66:67], v[84:85] op_sel:[1,0,0]
	v_pk_mul_f32 v[180:181], v[48:49], v[82:83] op_sel_hi:[0,1]
	v_pk_fma_f32 v[46:47], v[48:49], v[82:83], v[46:47] op_sel_hi:[0,1,1]
	v_exp_f32_e32 v67, v70
	v_exp_f32_e32 v66, v86
	v_mov_b32_e32 v48, v49
	v_pk_mul_f32 v[184:185], v[48:49], v[68:69] op_sel_hi:[0,1]
	v_pk_fma_f32 v[46:47], v[48:49], v[68:69], v[46:47] op_sel_hi:[0,1,1]
	v_exp_f32_e32 v49, v71
	v_exp_f32_e32 v48, v87
	v_exp_f32_e32 v69, v72
	v_exp_f32_e32 v68, v88
	v_exp_f32_e32 v71, v73
	v_exp_f32_e32 v70, v89
	v_exp_f32_e32 v73, v74
	v_exp_f32_e32 v72, v90
	s_waitcnt lgkmcnt(2)
	v_pk_fma_f32 v[46:47], v[42:43], v[66:67], v[46:47] op_sel_hi:[0,1,1]
	v_pk_mul_f32 v[188:189], v[42:43], v[66:67] op_sel_hi:[0,1]
	v_exp_f32_e32 v75, v75
	v_exp_f32_e32 v74, v91
	v_pk_mul_f32 v[204:205], v[42:43], v[48:49] op_sel:[1,0]
	v_pk_fma_f32 v[42:43], v[42:43], v[48:49], v[46:47] op_sel:[1,0,0]
	v_exp_f32_e32 v83, v76
	v_exp_f32_e32 v82, v92
	v_pk_mul_f32 v[208:209], v[44:45], v[68:69] op_sel_hi:[0,1]
	v_pk_fma_f32 v[42:43], v[44:45], v[68:69], v[42:43] op_sel_hi:[0,1,1]
	v_mov_b32_e32 v44, v45
	v_exp_f32_e32 v77, v77
	v_exp_f32_e32 v76, v93
	v_pk_fma_f32 v[42:43], v[44:45], v[70:71], v[42:43] op_sel_hi:[0,1,1]
	v_exp_f32_e32 v85, v78
	v_exp_f32_e32 v84, v94
	s_waitcnt lgkmcnt(1)
	v_pk_fma_f32 v[42:43], v[38:39], v[72:73], v[42:43] op_sel_hi:[0,1,1]
	v_exp_f32_e32 v79, v79
	v_exp_f32_e32 v78, v95
	v_pk_mul_f32 v[210:211], v[38:39], v[72:73] op_sel_hi:[0,1]
	v_pk_mul_f32 v[190:191], v[38:39], v[74:75] op_sel:[1,0]
	v_pk_fma_f32 v[38:39], v[38:39], v[74:75], v[42:43] op_sel:[1,0,0]
	v_exp_f32_e32 v87, v80
	v_exp_f32_e32 v86, v96
	v_pk_mul_f32 v[192:193], v[40:41], v[82:83] op_sel_hi:[0,1]
	v_pk_fma_f32 v[38:39], v[40:41], v[82:83], v[38:39] op_sel_hi:[0,1,1]
	v_mov_b32_e32 v40, v41
	v_exp_f32_e32 v81, v81
	v_exp_f32_e32 v80, v97
	v_pk_fma_f32 v[38:39], v[40:41], v[76:77], v[38:39] op_sel_hi:[0,1,1]
	s_waitcnt lgkmcnt(0)
	v_pk_fma_f32 v[38:39], v[34:35], v[84:85], v[38:39] op_sel_hi:[0,1,1]
	v_pk_mul_f32 v[186:187], v[34:35], v[84:85] op_sel_hi:[0,1]
	v_pk_mul_f32 v[174:175], v[34:35], v[78:79] op_sel:[1,0]
	v_pk_fma_f32 v[34:35], v[34:35], v[78:79], v[38:39] op_sel:[1,0,0]
	v_pk_mul_f32 v[178:179], v[36:37], v[86:87] op_sel_hi:[0,1]
	v_pk_fma_f32 v[34:35], v[36:37], v[86:87], v[34:35] op_sel_hi:[0,1,1]
	v_mov_b32_e32 v36, v37
	v_pk_fma_f32 v[34:35], v[36:37], v[80:81], v[34:35] op_sel_hi:[0,1,1]
	v_pk_mul_f32 v[206:207], v[44:45], v[70:71] op_sel_hi:[0,1]
	v_pk_mul_f32 v[182:183], v[40:41], v[76:77] op_sel_hi:[0,1]
	v_pk_mul_f32 v[168:169], v[36:37], v[80:81] op_sel_hi:[0,1]
	v_add_f32_e32 v170, v34, v35
	v_mov_b64_e32 v[34:35], v[50:51]
	v_mov_b64_e32 v[36:37], v[52:53]
	v_mov_b64_e32 v[38:39], v[54:55]
	v_mov_b64_e32 v[40:41], v[56:57]
	v_mov_b64_e32 v[42:43], v[58:59]
	v_mov_b64_e32 v[44:45], v[60:61]
	v_mov_b64_e32 v[46:47], v[62:63]
	v_mov_b64_e32 v[48:49], v[64:65]
	v_mov_b32_e32 v223, v224
	v_mov_b32_e32 v227, v222
	s_lshl_b32 s0, s16, 10
	s_sub_i32 s0, s2, s0
	v_add3_u32 v106, s0, v220, v0
	ds_read_b128 v[98:101], v106 offset:36992
	ds_read_b128 v[232:235], v106 offset:45696
	ds_read_b128 v[236:239], v106 offset:37024
	v_cvt_pk_bf16_f32 v102, v173, v177
	v_cvt_pk_bf16_f32 v103, v181, v185
	v_cvt_pk_bf16_f32 v104, v189, v205
	v_cvt_pk_bf16_f32 v105, v209, v207
	v_add_f32_e32 v222, v227, v170
	s_mov_b64 s[0:1], 0
	s_waitcnt lgkmcnt(2)
	v_mfma_f32_32x32x16_bf16 v[18:33], v[98:101], v[102:105], v[18:33]
	ds_read_b128 v[98:101], v106 offset:45728
	s_waitcnt lgkmcnt(2)
	v_mfma_f32_32x32x16_bf16 v[2:17], v[232:235], v[102:105], v[2:17]
	ds_read_b128 v[232:235], v106 offset:37056
	v_cvt_pk_bf16_f32 v102, v211, v191
	v_cvt_pk_bf16_f32 v103, v193, v183
	v_cvt_pk_bf16_f32 v104, v187, v175
	v_cvt_pk_bf16_f32 v105, v179, v169
	s_nop 0
	s_waitcnt lgkmcnt(2)
	v_mfma_f32_32x32x16_bf16 v[18:33], v[236:239], v[102:105], v[18:33]
	ds_read_b128 v[236:239], v106 offset:45760
	s_waitcnt lgkmcnt(2)
	v_mfma_f32_32x32x16_bf16 v[2:17], v[98:101], v[102:105], v[2:17]
	ds_read_b128 v[98:101], v106 offset:37088
	v_cvt_pk_bf16_f32 v102, v172, v176
	v_cvt_pk_bf16_f32 v103, v180, v184
	v_cvt_pk_bf16_f32 v104, v188, v204
	v_cvt_pk_bf16_f32 v105, v208, v206
	s_nop 0
	s_waitcnt lgkmcnt(2)
	v_mfma_f32_32x32x16_bf16 v[18:33], v[232:235], v[102:105], v[18:33]
	ds_read_b128 v[232:235], v106 offset:45792
	s_waitcnt lgkmcnt(2)
	v_mfma_f32_32x32x16_bf16 v[2:17], v[236:239], v[102:105], v[2:17]
	v_cvt_pk_bf16_f32 v102, v210, v190
	v_cvt_pk_bf16_f32 v103, v192, v182
	v_cvt_pk_bf16_f32 v104, v186, v174
	v_cvt_pk_bf16_f32 v105, v178, v168
	s_nop 0
	s_waitcnt lgkmcnt(1)
	v_mfma_f32_32x32x16_bf16 v[18:33], v[98:101], v[102:105], v[18:33]
	s_waitcnt lgkmcnt(0)
	v_mfma_f32_32x32x16_bf16 v[2:17], v[232:235], v[102:105], v[2:17]
	s_nop 15
	s_nop 3
	s_branch dilpv_join2

; #define ATT_GLOAD(dst, ptr) asm volatile("global_load_dwordx4 %0, %1, off" : "+v"(dst) : "v"(ptr) : "memory")
; template <int MODE> __device__ __forceinline__ void attn_unit(LAS unsigned char* lds, const AttnP& P, int b, int h, int qb) {
;     ...
;     for (int T = T_lo; T <= T_hi; ++T) {
;         const int buf = (T - T_lo) & 1; const bool more = T < T_hi;
;         if (more) { const bf16_t* kp = kg + (size_t)((T + 1) * 128) * NQK; const bf16_t* vp = vg + (T + 1) * 128;
;             ATT_GLOAD(ka, kp); ATT_GLOAD(kb2, kp + (size_t)64 * NQK); ATT_GLOAD(va, vp); ATT_GLOAD(vb2, vp + 64); }
;         compute(2 * T, buf * KSTEP, buf * VSTEP);
;         compute(2 * T + 1, buf * KSTEP + TILEB, buf * VSTEP + 128);
;         if (more) { const unsigned kw = ldsKw + (unsigned)((buf ^ 1) * KSTEP), vw = ldsVw + (unsigned)((buf ^ 1) * VSTEP);
;             asm volatile("s_waitcnt vmcnt(0)\n\tds_write_b128 %0, %1\n\tds_write_b128 %0, %2 offset:9216\n\tds_write_b128 %3, %4\n\tds_write_b128 %3, %5 offset:128"
;                          :: "v"(kw), "v"(ka), "v"(kb2), "v"(vw), "v"(va), "v"(vb2) : "memory"); }
;         asm volatile("s_waitcnt lgkmcnt(0)\n\ts_barrier" ::: "memory");
;     }
dilpv_join2:
	s_andn2_b64 vcc, exec, s[48:49]
	s_cbranch_vccnz .LBB0_744
